# plus the N=1024 weight conversion loop (ffn down, w_out, w_ukv): 8 row loads and gains in flight together instead of load then vmcnt(0) per row
# baseline (speedup 1.0000x reference)
; DI u16 bf1(float x) { return (u16)(pk2(x, 0.f) & 0xffffu); }
; DI void conv_tile(unsigned char* smem, const int wv, const float* __restrict__ src, u16* __restrict__ dst, int K, int N, int kind, const float* __restrict__ gain, int ktile, int ntile, bool kperm = false) {
;     ...
; #pragma unroll 4
;   for (int i = 0; i < 8; ++i) {
;     const int k = kq * 8 + i;
;     float v = 0.f;
;     if (n < N) { v = src[(size_t)(k0 + k) * N + n]; if (gain) v *= gain[k0 + k]; }
;     T[nl][k] = bf1(v);
;   }
.LBB0_963:
.LBB0_964:
	v_add_co_u32_e32 v206, vcc, 0xffffe000, v2
	s_nop 1
	v_addc_co_u32_e32 v207, vcc, -1, v3, vcc
	v_add_co_u32_e32 v208, vcc, 0x2000, v2
	s_nop 1
	v_addc_co_u32_e32 v209, vcc, 0, v3, vcc
	v_add_co_u32_e32 v210, vcc, 0x4000, v2
	s_nop 1
	v_addc_co_u32_e32 v211, vcc, 0, v3, vcc
	global_load_dword v212, v[206:207], off offset:-4096
	global_load_dword v213, v[206:207], off
	global_load_dword v214, v[2:3], off offset:-4096
	global_load_dword v215, v[2:3], off
	global_load_dword v216, v[208:209], off offset:-4096
	global_load_dword v217, v[208:209], off
	global_load_dword v218, v[210:211], off offset:-4096
	global_load_dword v219, v[210:211], off
	v_readlane_b32 s0, v252, 61
	v_readlane_b32 s1, v252, 62
	s_andn2_b64 vcc, exec, s[0:1]
	s_nop 0
	v_cndmask_b32_e64 v103, 0, 1, s[0:1]
	v_cmp_ne_u32_e64 s[92:93], 1, v103
	s_cbranch_vccnz .Lconv2_nogain
	global_load_dword v220, v[100:101], off
	global_load_dword v221, v[0:1], off offset:4
	global_load_dword v222, v[0:1], off offset:8
	global_load_dword v223, v[0:1], off offset:12
	global_load_dword v224, v[100:101], off offset:16
	global_load_dword v225, v[0:1], off offset:20
	global_load_dword v226, v[0:1], off offset:24
	global_load_dword v227, v[0:1], off offset:28
	s_waitcnt vmcnt(0)
	v_mul_f32_e32 v212, v212, v220
	v_mul_f32_e32 v213, v213, v221
	v_mul_f32_e32 v214, v214, v222
	v_mul_f32_e32 v215, v215, v223
	v_mul_f32_e32 v216, v216, v224
	v_mul_f32_e32 v217, v217, v225
	v_mul_f32_e32 v218, v218, v226
	v_mul_f32_e32 v219, v219, v227
.Lconv2_nogain:
	s_waitcnt vmcnt(0)
	v_cvt_pk_bf16_f32 v212, v212, v213
	v_cvt_pk_bf16_f32 v214, v214, v215
	v_cvt_pk_bf16_f32 v216, v216, v217
	v_cvt_pk_bf16_f32 v218, v218, v219
	ds_write_b32 v167, v212
	ds_write_b32 v167, v214 offset:4
	ds_write_b32 v167, v216 offset:8
	ds_write_b32 v167, v218 offset:12
	v_add_u32_e32 v167, 16, v167
	s_mov_b64 s[2:3], 32
	s_mov_b64 s[0:1], 0x4000
	s_branch .LBB0_975
